# ssd prologue: scalar-table loads issued before state loads, B/xT block-0 loads right after, single counted wait
# baseline (speedup 1.0000x reference)
.LBB0_199:
	s_cmpk_gt_i32 s16, 0x3ff
	s_mov_b64 s[0:1], -1
	s_cbranch_scc0 .LBB0_221
	s_add_i32 s8, s16, 0xfffffc00
	s_and_b32 s9, s16, 3
	s_bfe_i32 s12, s16, 0x10008
	v_mov_b32_e32 v176, v167
	s_lshr_b32 s11, s8, 2
	s_and_b32 s12, s12, 3
	s_lshl_b32 s17, s9, 9
	v_readfirstlane_b32 s20, v176
	v_ashrrev_i32_e32 v169, 3, v176
	s_xor_b32 s13, s12, s11
	s_ashr_i32 s11, s20, 6
	s_lshr_b32 s19, s8, 4
	s_lshl_b32 s8, s9, 3
	v_add_u32_e32 v10, s17, v169
	v_mov_b64_e32 v[8:9], s[82:83]
	s_add_i32 s34, s11, s8
	v_lshlrev_b32_e32 v0, 3, v176
	s_lshl_b32 s12, s9, 7
	s_lshl_b32 s28, s9, 8
	v_mad_i64_i32 v[8:9], s[8:9], v10, s37, v[8:9]
	v_and_b32_e32 v166, 56, v0
	s_lshl_b32 s8, s19, 9
	s_mov_b32 s9, s29
	v_lshl_add_u64 v[8:9], v[8:9], 0, s[8:9]
	v_lshlrev_b32_e32 v10, 1, v166
	v_mov_b32_e32 v11, v157
	v_lshl_add_u64 v[32:33], v[8:9], 0, v[10:11]
	s_mov_b32 s8, 0x102000
	v_add_co_u32_e32 v12, vcc, s8, v32
	s_mov_b32 s8, 0x204000
	s_nop 0
	v_addc_co_u32_e32 v13, vcc, 0, v33, vcc
	v_add_co_u32_e32 v16, vcc, s8, v32
	s_mov_b32 s8, 0x306000
	s_nop 0
	v_addc_co_u32_e32 v17, vcc, 0, v33, vcc
	v_add_co_u32_e32 v20, vcc, s8, v32
	s_mov_b32 s8, 0x408000
	s_nop 0
	v_addc_co_u32_e32 v21, vcc, 0, v33, vcc
	v_add_co_u32_e32 v24, vcc, s8, v32
	s_mov_b32 s8, 0x50a000
	s_nop 0
	v_addc_co_u32_e32 v25, vcc, 0, v33, vcc
	v_add_co_u32_e32 v28, vcc, s8, v32
	s_mov_b32 s8, 0x60c000
	s_nop 0
	v_addc_co_u32_e32 v29, vcc, 0, v33, vcc
	v_add_co_u32_e32 v34, vcc, s8, v32
	s_mov_b32 s8, 0x70e000
	s_nop 0
	v_addc_co_u32_e32 v35, vcc, 0, v33, vcc
	v_add_co_u32_e32 v36, vcc, s8, v32
	s_lshl_b32 s8, s34, 5
	s_add_i32 s8, s8, s19
	s_lshl_b32 s0, s14, 4
	s_and_b32 s10, s15, 3
	s_ashr_i32 s9, s8, 31
	s_and_b32 s0, s0, 0xffffff00
	s_lshl_b32 s1, s10, 16
	s_and_b32 s18, s13, 3
	s_lshl_b64 s[8:9], s[8:9], 14
	v_readlane_b32 s24, v251, 49
	v_and_b32_e32 v171, 15, v176
	v_readlane_b32 s25, v251, 50
	s_add_u32 s8, s24, s8
	v_ashrrev_i32_e32 v177, 4, v176
	s_addc_u32 s9, s25, s9
	v_lshlrev_b32_e32 v40, 8, v171
	v_mov_b32_e32 v41, v157
	v_and_b32_e32 v168, 0x78, v0
	v_lshl_add_u32 v0, s19, 8, v177
	v_lshl_add_u64 v[40:41], s[8:9], 0, v[40:41]
	v_and_b32_e32 v80, 48, v176
	v_mov_b32_e32 v81, v157
	s_lshl_b32 s19, s13, 6
	v_addc_co_u32_e32 v37, vcc, 0, v33, vcc
	v_lshl_add_u64 v[40:41], v[40:41], 0, v[80:81]
	s_movk_i32 s8, 0x2000
	v_add_u32_e32 v42, s19, v177
	s_waitcnt lgkmcnt(0)
	v_ashrrev_i32_e32 v1, 31, v0
	v_add_co_u32_e32 v60, vcc, s8, v40
	v_ashrrev_i32_e32 v43, 31, v42
	v_lshlrev_b64 v[2:3], 10, v[0:1]
	v_add_u32_e32 v0, 32, v0
	v_addc_co_u32_e32 v61, vcc, 0, v41, vcc
	s_movk_i32 s8, 0x3000
	v_lshlrev_b64 v[52:53], 10, v[42:43]
	v_add_u32_e32 v42, 32, v42
	v_readlane_b32 s22, v251, 30
	v_ashrrev_i32_e32 v1, 31, v0
	v_add_co_u32_e32 v86, vcc, s8, v40
	v_readlane_b32 s8, v251, 28
	v_ashrrev_i32_e32 v43, 31, v42
	v_readlane_b32 s23, v251, 31
	v_lshlrev_b64 v[0:1], 10, v[0:1]
	v_readlane_b32 s9, v251, 29
	v_lshlrev_b64 v[42:43], 10, v[42:43]
	v_lshl_add_u64 v[2:3], s[22:23], 0, v[2:3]
	v_lshl_add_u64 v[0:1], s[22:23], 0, v[0:1]
	v_addc_co_u32_e32 v87, vcc, 0, v41, vcc
	v_lshl_add_u64 v[52:53], s[8:9], 0, v[52:53]
	v_lshl_add_u64 v[42:43], s[8:9], 0, v[42:43]
	s_movk_i32 s8, 0x1000
	v_lshl_add_u64 v[2:3], v[2:3], 0, s[28:29]
	v_lshlrev_b32_e32 v156, 1, v168
	v_lshl_add_u64 v[0:1], v[0:1], 0, s[28:29]
	v_lshl_add_u64 v[52:53], v[52:53], 0, s[28:29]
	v_lshl_add_u64 v[42:43], v[42:43], 0, s[28:29]
	v_add_co_u32_e32 v62, vcc, s8, v40
	v_lshl_add_u64 v[2:3], v[2:3], 0, v[156:157]
	v_lshl_add_u64 v[4:5], v[0:1], 0, v[156:157]
	v_lshl_add_u64 v[52:53], v[52:53], 0, v[156:157]
	v_lshl_add_u64 v[42:43], v[42:43], 0, v[156:157]
	v_addc_co_u32_e32 v63, vcc, 0, v41, vcc
	s_nop 0
	s_lshl_b32 s9, s11, 13
	s_add_i32 s9, s1, s9
	s_add_i32 s9, s9, s0
	s_add_i32 s9, s9, 0x80000
	s_add_i32 s8, s18, 1
	v_and_b32_e32 v82, 63, v176
	v_or_b32_e32 v82, s9, v82
	v_add_u32_e32 v84, 0xfffc0000, v82
	v_ashrrev_i32_e32 v85, 31, v84
	v_lshl_add_u64 v[84:85], v[84:85], 2, s[26:27]
	v_ashrrev_i32_e32 v83, 31, v82
	global_load_dword v236, v[84:85], off
	v_lshl_add_u64 v[84:85], v[82:83], 2, s[26:27]
	global_load_dword v237, v[84:85], off
	v_add_u32_e32 v82, 64, v82
	s_cmp_lt_u32 s8, 2
	s_cbranch_scc1 .Lsa_i
	v_add_u32_e32 v84, 0xfffc0000, v82
	v_ashrrev_i32_e32 v85, 31, v84
	v_lshl_add_u64 v[84:85], v[84:85], 2, s[26:27]
	v_ashrrev_i32_e32 v83, 31, v82
	global_load_dword v238, v[84:85], off
	v_lshl_add_u64 v[84:85], v[82:83], 2, s[26:27]
	global_load_dword v239, v[84:85], off
	v_add_u32_e32 v82, 64, v82
	s_cmp_lt_u32 s8, 3
	s_cbranch_scc1 .Lsa_i
	v_add_u32_e32 v84, 0xfffc0000, v82
	v_ashrrev_i32_e32 v85, 31, v84
	v_lshl_add_u64 v[84:85], v[84:85], 2, s[26:27]
	v_ashrrev_i32_e32 v83, 31, v82
	global_load_dword v240, v[84:85], off
	v_lshl_add_u64 v[84:85], v[82:83], 2, s[26:27]
	global_load_dword v241, v[84:85], off
	v_add_u32_e32 v82, 64, v82
	s_cmp_lt_u32 s8, 4
	s_cbranch_scc1 .Lsa_i
	v_add_u32_e32 v84, 0xfffc0000, v82
	v_ashrrev_i32_e32 v85, 31, v84
	v_lshl_add_u64 v[84:85], v[84:85], 2, s[26:27]
	v_ashrrev_i32_e32 v83, 31, v82
	global_load_dword v242, v[84:85], off
	v_lshl_add_u64 v[84:85], v[82:83], 2, s[26:27]
	global_load_dword v243, v[84:85], off
	v_add_u32_e32 v82, 64, v82
.Lsa_i:
	global_load_dwordx4 v[64:67], v[40:41], off
	global_load_dwordx4 v[48:51], v[40:41], off offset:64
	global_load_dwordx4 v[44:47], v[40:41], off offset:128
	global_load_dwordx4 v[88:91], v[40:41], off offset:192
	global_load_dwordx4 v[100:103], v[86:87], off offset:192
	global_load_dwordx4 v[82:85], v[52:53], off
	global_load_dwordx4 v[68:71], v[60:61], off offset:-4096
	global_load_dwordx4 v[116:119], v[42:43], off
	global_load_dwordx4 v[56:59], v[62:63], off offset:64
	s_nop 0
	global_load_dwordx4 v[40:43], v[62:63], off offset:128
	global_load_dwordx4 v[72:75], v[60:61], off
	global_load_dwordx4 v[52:55], v[60:61], off offset:64
	global_load_dwordx4 v[112:115], v[60:61], off offset:128
	global_load_dwordx4 v[94:97], v[60:61], off offset:192
	global_load_dwordx4 v[104:107], v[62:63], off offset:192
	global_load_dwordx4 v[76:79], v[86:87], off
	s_nop 0
	global_load_dwordx4 v[60:63], v[86:87], off offset:64
	global_load_dwordx4 v[108:111], v[86:87], off offset:128
	global_load_dwordx4 v[0:3], v[2:3], off
	s_nop 0
	global_load_dwordx4 v[4:7], v[4:5], off
	s_nop 0
	global_load_dwordx4 v[8:11], v[32:33], off
	s_nop 0
	global_load_dwordx4 v[12:15], v[12:13], off
	s_nop 0
	global_load_dwordx4 v[16:19], v[16:17], off
	s_nop 0
	global_load_dwordx4 v[20:23], v[20:21], off
	s_nop 0
	global_load_dwordx4 v[24:27], v[24:25], off
	s_nop 0
	global_load_dwordx4 v[28:31], v[28:29], off
	s_nop 0
	global_load_dwordx4 v[32:35], v[34:35], off
	s_nop 0
	global_load_dwordx4 v[36:39], v[36:37], off
	s_lshl_b32 s9, s11, 10
	s_add_i32 s21, s9, 16
	s_lshl_b32 s9, s11, 13
	s_movk_i32 s24, 0x110
	s_add_i32 s1, s1, s9
	v_mul_lo_u32 v81, v177, s24
	s_add_i32 s1, s1, s0
	v_and_b32_e32 v86, 63, v176
	v_bfe_u32 v172, v176, 4, 2
	v_add3_u32 v174, 16, v81, v156
	s_add_i32 s13, s21, 0x4400
	s_add_i32 s1, s1, 0x80000
	v_lshlrev_b32_e32 v173, 3, v172
	s_waitcnt vmcnt(10)
	ds_write_b128 v174, v[82:85] offset:33792
	ds_write_b128 v174, v[116:119] offset:42496
	s_add_i32 s8, s18, 1
	v_lshl_add_u32 v81, v86, 2, s13
.LBB0_201:
	ds_write2st64_b32 v81, v236, v237 offset1:32
	s_cmp_lt_u32 s8, 2
	s_cbranch_scc1 .Lsa_d
	v_add_u32_e32 v81, 0x100, v81
	ds_write2st64_b32 v81, v238, v239 offset1:32
	s_cmp_lt_u32 s8, 3
	s_cbranch_scc1 .Lsa_d
	v_add_u32_e32 v81, 0x100, v81
	ds_write2st64_b32 v81, v240, v241 offset1:32
	s_cmp_lt_u32 s8, 4
	s_cbranch_scc1 .Lsa_d
	v_add_u32_e32 v81, 0x100, v81
	ds_write2st64_b32 v81, v242, v243 offset1:32
.Lsa_d:
	v_lshlrev_b32_e32 v178, 1, v173
	v_mov_b32_e32 v86, 0x1100
	v_add_u32_e32 v170, 16, v178
	v_mad_u32_u24 v175, v171, s24, v86
	v_mad_u32_u24 v81, v171, s24, v170
	v_add_u32_e32 v86, v170, v175
	s_waitcnt lgkmcnt(0)
	s_barrier
	ds_read_b128 v[82:85], v81 offset:33792
	ds_read_b128 v[120:123], v86 offset:33792
	ds_read_b128 v[128:131], v86 offset:38144
	ds_read_b128 v[220:223], v86 offset:38208
	ds_read_b128 v[136:139], v86 offset:42496
	ds_read_b128 v[224:227], v86 offset:42560
	s_waitcnt lgkmcnt(5)
	v_mfma_f32_16x16x32_bf16 v[116:119], v[82:85], v[64:67], 0
	s_mov_b32 s1, s29
	s_lshl_b64 s[8:9], s[0:1], 1
	s_lshl_b32 s1, s18, 8
	s_waitcnt lgkmcnt(4)
	v_mfma_f32_16x16x32_bf16 v[124:127], v[120:123], v[64:67], 0
	s_add_i32 s1, s21, s1
	v_add_u32_e32 v156, s1, v80
	s_lshl_b32 s12, s12, 1
	s_waitcnt lgkmcnt(3)
	v_mfma_f32_16x16x32_bf16 v[132:135], v[128:131], v[64:67], 0
	s_add_u32 s22, s22, s12
	s_movk_i32 s21, 0x90
	s_addc_u32 s23, s23, 0
	s_waitcnt lgkmcnt(1)
	v_mfma_f32_16x16x32_bf16 v[64:67], v[136:139], v[64:67], 0
	s_ashr_i32 s12, s20, 3
	v_readlane_b32 s25, v253, 62
	s_and_b32 s12, s12, -16
	v_mfma_f32_16x16x32_bf16 v[140:143], v[82:85], v[68:71], 0
	s_andn2_b32 s20, s20, 63
	v_or_b32_e32 v203, 16, v171
	v_or_b32_e32 v181, 32, v171
	v_mfma_f32_16x16x32_bf16 v[144:147], v[120:123], v[68:71], 0
	v_or_b32_e32 v180, 48, v171
	s_lshl_b32 s11, s11, 1
	s_and_b32 s11, s11, 2
	v_mfma_f32_16x16x32_bf16 v[148:151], v[128:131], v[68:71], 0
	v_mul_u32_u24_e32 v179, 0x110, v171
	v_cmp_lt_u32_e64 s[38:39], v173, v171
	v_cmp_le_u32_e64 s[52:53], v173, v203
	v_mfma_f32_16x16x32_bf16 v[68:71], v[136:139], v[68:71], 0
	v_cmp_lt_u32_e64 s[54:55], v173, v203
	v_mfma_f32_16x16x32_bf16 v[152:155], v[82:85], v[72:75], 0
	v_mfma_f32_16x16x32_bf16 v[204:207], v[120:123], v[72:75], 0
	v_mfma_f32_16x16x32_bf16 v[208:211], v[128:131], v[72:75], 0
	v_mfma_f32_16x16x32_bf16 v[72:75], v[136:139], v[72:75], 0
	v_mfma_f32_16x16x32_bf16 v[82:85], v[82:85], v[76:79], 0
	v_mfma_f32_16x16x32_bf16 v[120:123], v[120:123], v[76:79], 0
	v_mfma_f32_16x16x32_bf16 v[212:215], v[128:131], v[76:79], 0
	v_mfma_f32_16x16x32_bf16 v[76:79], v[136:139], v[76:79], 0
	ds_read_b128 v[136:139], v81 offset:33856
	s_waitcnt lgkmcnt(1)
	v_mfma_f32_16x16x32_bf16 v[232:235], v[224:227], v[56:59], v[68:71]
	v_mfma_f32_16x16x32_bf16 v[68:71], v[220:223], v[60:63], v[212:215]
	s_nop 2
	ds_read_b128 v[212:215], v81 offset:33920
	s_waitcnt lgkmcnt(1)
	v_mfma_f32_16x16x32_bf16 v[216:219], v[136:139], v[48:51], v[116:119]
	s_nop 2
	ds_read_b128 v[116:119], v86 offset:33856
	s_waitcnt lgkmcnt(0)
	v_mfma_f32_16x16x32_bf16 v[124:127], v[116:119], v[48:51], v[124:127]
	v_mfma_f32_16x16x32_bf16 v[132:135], v[220:223], v[48:51], v[132:135]
	v_mfma_f32_16x16x32_bf16 v[48:51], v[224:227], v[48:51], v[64:67]
	v_mfma_f32_16x16x32_bf16 v[64:67], v[136:139], v[56:59], v[140:143]
	s_nop 2
	ds_read_b128 v[140:143], v86 offset:33920
	v_mfma_f32_16x16x32_bf16 v[228:231], v[116:119], v[56:59], v[144:147]
	v_mfma_f32_16x16x32_bf16 v[148:151], v[220:223], v[56:59], v[148:151]
	v_mfma_f32_16x16x32_bf16 v[152:155], v[136:139], v[52:55], v[152:155]
	v_mfma_f32_16x16x32_bf16 v[204:207], v[116:119], v[52:55], v[204:207]
	v_mfma_f32_16x16x32_bf16 v[144:147], v[220:223], v[52:55], v[208:211]
	v_mfma_f32_16x16x32_bf16 v[128:131], v[224:227], v[52:55], v[72:75]
	ds_read_b128 v[52:55], v81 offset:33984
	v_mfma_f32_16x16x32_bf16 v[208:211], v[136:139], v[60:63], v[82:85]
	v_mfma_f32_16x16x32_bf16 v[56:59], v[116:119], v[60:63], v[120:123]
	v_mfma_f32_16x16x32_bf16 v[116:119], v[224:227], v[60:63], v[76:79]
	s_waitcnt lgkmcnt(1)
	v_mfma_f32_16x16x32_bf16 v[60:63], v[140:143], v[44:47], v[124:127]
	s_nop 0
	ds_read_b128 v[76:79], v86 offset:38272
	s_nop 0
	ds_read_b128 v[124:127], v86 offset:42624
	v_mfma_f32_16x16x32_bf16 v[216:219], v[212:215], v[44:47], v[216:219]
	s_waitcnt lgkmcnt(1)
	v_mfma_f32_16x16x32_bf16 v[72:75], v[76:79], v[44:47], v[132:135]
	s_waitcnt lgkmcnt(0)
	v_mfma_f32_16x16x32_bf16 v[120:123], v[124:127], v[44:47], v[48:51]
	v_mfma_f32_16x16x32_bf16 v[44:47], v[212:215], v[40:43], v[64:67]
	v_mfma_f32_16x16x32_bf16 v[64:67], v[140:143], v[40:43], v[228:231]
	v_mfma_f32_16x16x32_bf16 v[82:85], v[76:79], v[40:43], v[148:151]
	v_mfma_f32_16x16x32_bf16 v[132:135], v[124:127], v[40:43], v[232:235]
	v_mfma_f32_16x16x32_bf16 v[220:223], v[212:215], v[112:115], v[152:155]
	ds_read_b128 v[40:43], v156 offset:17408
	s_nop 1
	ds_read_b128 v[152:155], v86 offset:33984
	ds_read_b128 v[148:151], v86 offset:38336
	ds_read_b128 v[136:139], v86 offset:42688
	s_waitcnt lgkmcnt(3)
	v_mul_f32_e32 v40, 0x3fb8aa3b, v40
	v_exp_f32_e32 v80, v40
	v_mul_f32_e32 v40, 0x3fb8aa3b, v41
	v_mul_f32_e32 v41, 0x3fb8aa3b, v42
	v_exp_f32_e32 v86, v41
	v_mul_f32_e32 v41, 0x3fb8aa3b, v43
	v_mfma_f32_16x16x32_bf16 v[208:211], v[212:215], v[108:111], v[208:211]
	v_exp_f32_e32 v87, v41
	v_exp_f32_e32 v81, v40
	v_mfma_f32_16x16x32_bf16 v[48:51], v[52:55], v[88:91], v[216:219]
	v_mfma_f32_16x16x32_bf16 v[44:47], v[52:55], v[104:107], v[44:47]
	v_mfma_f32_16x16x32_bf16 v[212:215], v[52:55], v[94:97], v[220:223]
	s_nop 5
	v_mul_f32_e64 v42, v50, v86
	v_mul_f32_e64 v43, v51, v87
	v_pk_mul_f32 v[50:51], v[46:47], v[86:87]
	v_pk_mul_f32 v[40:41], v[48:49], v[80:81]
	v_mfma_f32_16x16x32_bf16 v[52:55], v[52:55], v[100:103], v[208:211]
	v_mul_f32_e64 v48, v44, v80
	v_mul_f32_e64 v49, v45, v81
	v_pk_mul_f32 v[46:47], v[214:215], v[86:87]
	ds_read_b128 v[214:217], v156 offset:17472
	v_mfma_f32_16x16x32_bf16 v[204:207], v[140:143], v[112:115], v[204:207]
	v_mul_f32_e64 v44, v212, v80
	v_mul_f32_e64 v45, v213, v81
	s_nop 0
	v_pk_mul_f32 v[54:55], v[54:55], v[86:87]
	v_pk_mul_f32 v[52:53], v[52:53], v[80:81]
	v_mfma_f32_16x16x32_bf16 v[140:143], v[140:143], v[108:111], v[56:59]
	s_waitcnt lgkmcnt(0)
	v_mul_f32_e32 v80, 0x3fb8aa3b, v214
	v_mul_f32_e32 v81, 0x3fb8aa3b, v215
	v_exp_f32_e32 v80, v80
	v_mul_f32_e32 v56, 0x3fb8aa3b, v216
	v_exp_f32_e32 v86, v56
	v_mfma_f32_16x16x32_bf16 v[56:59], v[152:155], v[88:91], v[60:63]
	v_exp_f32_e32 v81, v81
	s_nop 1
	v_mul_f32_e32 v60, 0x3fb8aa3b, v217
	v_exp_f32_e32 v87, v60
	v_mfma_f32_16x16x32_bf16 v[60:63], v[152:155], v[104:107], v[64:67]
	s_nop 1
	v_mul_f32_e64 v56, v56, v80
	v_mul_f32_e64 v57, v57, v81
	v_pk_mul_f32 v[58:59], v[58:59], v[86:87]
	v_mfma_f32_16x16x32_bf16 v[64:67], v[152:155], v[94:97], v[204:207]
	s_nop 2
	ds_read_b128 v[204:207], v156 offset:17536
	v_mfma_f32_16x16x32_bf16 v[140:143], v[152:155], v[100:103], v[140:143]
	v_mul_f32_e64 v60, v60, v80
	v_mul_f32_e64 v61, v61, v81
	s_nop 0
	v_pk_mul_f32 v[64:65], v[64:65], v[80:81]
	v_pk_mul_f32 v[62:63], v[62:63], v[86:87]
	v_mfma_f32_16x16x32_bf16 v[152:155], v[76:79], v[108:111], v[68:71]
	s_waitcnt lgkmcnt(0)
	v_mul_f32_e32 v92, 0x3fb8aa3b, v204
	v_exp_f32_e32 v92, v92
	v_pk_mul_f32 v[80:81], v[140:141], v[80:81]
	v_mul_f32_e32 v68, 0x3fb8aa3b, v205
	v_mfma_f32_16x16x32_bf16 v[144:147], v[76:79], v[112:115], v[144:147]
	v_exp_f32_e32 v93, v68
	v_mul_f32_e32 v76, 0x3fb8aa3b, v206
	v_exp_f32_e32 v98, v76
	v_mfma_f32_16x16x32_bf16 v[68:71], v[148:151], v[88:91], v[72:75]
	v_mul_f32_e64 v66, v66, v86
	v_mul_f32_e64 v67, v67, v87
	s_nop 0
	v_mul_f32_e32 v72, 0x3fb8aa3b, v207
	v_exp_f32_e32 v99, v72
	v_mfma_f32_16x16x32_bf16 v[72:75], v[148:151], v[104:107], v[82:85]
	s_nop 1
	v_mul_f32_e64 v76, v68, v92
	v_mul_f32_e64 v77, v69, v93
	v_pk_mul_f32 v[78:79], v[70:71], v[98:99]
	v_pk_mul_f32 v[82:83], v[142:143], v[86:87]
	ds_read_b128 v[140:143], v156 offset:17600
	v_mfma_f32_16x16x32_bf16 v[68:71], v[148:151], v[94:97], v[144:147]
	v_mul_f32_e64 v72, v72, v92
	v_mul_f32_e64 v73, v73, v93
	v_lshlrev_b32_e32 v156, 1, v168
	v_pk_mul_f32 v[74:75], v[74:75], v[98:99]
	v_mfma_f32_16x16x32_bf16 v[84:87], v[148:151], v[100:103], v[152:155]
	v_lshl_add_u32 v150, v173, 2, 16
	s_nop 1
	v_pk_mul_f32 v[68:69], v[68:69], v[92:93]
	v_pk_mul_f32 v[70:71], v[70:71], v[98:99]
	v_mfma_f32_16x16x32_bf16 v[112:115], v[124:127], v[112:115], v[128:131]
	v_lshl_add_u32 v152, v172, 5, s13
	s_nop 0
	v_pk_mul_f32 v[84:85], v[84:85], v[92:93]
	s_waitcnt lgkmcnt(0)
	v_mul_f32_e32 v92, 0x3fb8aa3b, v140
	v_exp_f32_e32 v128, v92
	v_mul_f32_e32 v92, 0x3fb8aa3b, v141
	v_exp_f32_e32 v129, v92
	v_mfma_f32_16x16x32_bf16 v[104:107], v[136:139], v[104:107], v[132:135]
	v_mul_f32_e32 v92, 0x3fb8aa3b, v142
	v_pk_mul_f32 v[86:87], v[86:87], v[98:99]
	v_add_u32_e32 v168, v150, v179
	v_mfma_f32_16x16x32_bf16 v[108:111], v[124:127], v[108:111], v[116:119]
	v_lshlrev_b32_e32 v132, 1, v166
	v_lshl_add_u64 v[134:135], s[22:23], 0, v[156:157]
	s_nop 0
	v_exp_f32_e32 v116, v92
	v_mul_f32_e32 v92, 0x3fb8aa3b, v143
	v_exp_f32_e32 v117, v92
	v_pk_mul_f32 v[92:93], v[104:105], v[128:129]
	v_mul_lo_u32 v104, v169, s21
	v_add3_u32 v133, s25, v104, v132
	v_or_b32_e32 v104, s12, v171
	v_mfma_f32_16x16x32_bf16 v[88:91], v[136:139], v[88:91], v[120:123]
	v_lshlrev_b32_e32 v105, 2, v171
	v_add_u32_e32 v151, s1, v105
	s_lshl_b32 s1, s18, 7
	v_mfma_f32_16x16x32_bf16 v[96:99], v[136:139], v[94:97], v[112:115]
	v_mul_f32_e64 v94, v106, v116
	v_mul_f32_e64 v95, v107, v117
	v_add_u32_e32 v106, 16, v105
	v_or_b32_e32 v105, 3, v173
	v_mfma_f32_16x16x32_bf16 v[100:103], v[136:139], v[100:103], v[108:111]
	v_mad_u64_u32 v[136:137], s[22:23], v104, s24, v[170:171]
	v_lshl_or_b32 v104, v172, 2, s12
	s_nop 0
	v_or_b32_e32 v108, s20, v171
	v_mul_lo_u32 v112, v104, s24
	v_or_b32_e32 v104, 2, v173
	v_cmp_le_u32_e64 s[40:41], v104, v171
	v_cmp_le_u32_e64 s[42:43], v105, v171
	v_cmp_le_u32_e64 s[56:57], v104, v203
	v_cmp_le_u32_e64 s[58:59], v105, v203
	v_mul_lo_u32 v137, v108, s21
	v_or_b32_e32 v104, 32, v173
	v_or_b32_e32 v105, 33, v173
	v_or_b32_e32 v108, 34, v173
	v_cmp_le_u32_e64 s[68:69], v105, v181
	v_cmp_le_u32_e64 s[70:71], v108, v181
	v_cmp_le_u32_e64 s[82:83], v104, v180
	v_cmp_le_u32_e64 s[84:85], v105, v180
	v_cmp_le_u32_e64 s[86:87], v108, v180
	s_add_u32 s21, s1, 0x80
	v_add3_u32 v138, v177, s0, 64
	v_mad_i64_i32 v[104:105], s[0:1], v169, s37, 0
	v_mov_b32_e32 v108, 0x810000
	s_or_b32 s12, s11, 1
	v_mad_u64_u32 v[104:105], s[0:1], s10, v108, v[104:105]
	v_pk_mul_f32 v[90:91], v[90:91], v[116:117]
	v_pk_mul_f32 v[98:99], v[98:99], v[116:117]
	v_pk_mul_f32 v[102:103], v[102:103], v[116:117]
	v_lshl_or_b32 v109, s11, 4, v171
	v_lshl_or_b32 v110, s12, 4, v171
	v_or_b32_e32 v113, 4, v173
	v_or_b32_e32 v114, 5, v173
	v_or_b32_e32 v115, 6, v173
	v_or_b32_e32 v116, 7, v173
	v_and_b32_e32 v108, 7, v176
	s_add_u32 s0, s4, s8
	v_add_u32_e32 v107, s25, v178
	v_mul_u32_u24_e32 v109, 0x110, v109
	v_mul_u32_u24_e32 v110, 0x110, v110
	v_lshl_add_u32 v111, s11, 6, v106
	v_lshl_add_u32 v106, s12, 6, v106
	v_cmp_le_u32_e64 s[44:45], v113, v171
	v_cmp_le_u32_e64 s[46:47], v114, v171
	v_cmp_le_u32_e64 s[48:49], v115, v171
	v_cmp_le_u32_e64 s[50:51], v116, v171
	v_cmp_le_u32_e64 s[60:61], v113, v203
	v_cmp_le_u32_e64 s[62:63], v114, v203
	v_cmp_le_u32_e64 s[64:65], v115, v203
	v_cmp_le_u32_e64 s[66:67], v116, v203
	v_or_b32_e32 v113, 35, v173
	v_or_b32_e32 v114, 36, v173
	v_or_b32_e32 v115, 37, v173
	v_or_b32_e32 v116, 38, v173
	v_or_b32_e32 v117, 39, v173
	v_lshl_or_b32 v104, v108, 4, v104
	s_addc_u32 s1, s5, s9
	v_pk_mul_f32 v[88:89], v[88:89], v[128:129]
	v_pk_mul_f32 v[96:97], v[96:97], v[128:129]
	v_pk_mul_f32 v[100:101], v[100:101], v[128:129]
	v_cmp_le_u32_e64 s[24:25], v173, v171
	v_cmp_le_u32_e64 s[72:73], v113, v181
	v_cmp_le_u32_e64 s[74:75], v114, v181
	v_cmp_le_u32_e64 s[76:77], v115, v181
	v_cmp_le_u32_e64 s[78:79], v116, v181
	v_cmp_le_u32_e64 s[80:81], v117, v181
	v_cmp_le_u32_e64 s[88:89], v113, v180
	v_cmp_le_u32_e64 s[90:91], v114, v180
	v_cmp_le_u32_e64 s[92:93], v115, v180
	v_cmp_le_u32_e64 s[94:95], v116, v180
	v_cmp_le_u32_e64 s[96:97], v117, v180
	v_lshl_add_u64 v[140:141], s[0:1], 0, v[104:105]
	s_mov_b32 s22, 0
	s_mov_b64 s[8:9], 0
	v_add_u32_e32 v153, v170, v109
	v_add_u32_e32 v154, v170, v110
	v_add_u32_e32 v155, v111, v112
	v_add_u32_e32 v156, v106, v112
	v_add_u32_e32 v170, v107, v137
	s_branch .LBB0_204
